# odd XCDs (blockIdx bit0) run dil before diff in the attention phase
# baseline (speedup 1.0000x reference)
; __device__ __forceinline__ void attn_phase(unsigned char* ws, int l, LAS unsigned char* lds, int G) {
;     ...
;     for (int u = vb; u < 768; u += G) {
;         const int pair = u >> 6, qb = u & 63;
;         diff_unit(lds, proj, par + P_SUBN + l * 64, pair >> 2, pair & 3, qb, lam, osc);
;     }
;     __syncthreads();
;     for (int bu = vb; bu < 1152; bu += G) {
;         const int sh = bu >> 6, rem = bu & 63, T0 = (rem >> 1) * 512, rho = (rem & 1) * 8 + wid;
;         dil_unit(lds, proj, sh / 6, sh % 6, T0, rho);
;     }
.LBB0_519:
	s_bitcmp1_b32 s14, 0
	s_cbranch_scc0 .Lsw0_diff
	s_mov_b32 s92, 1
	s_mov_b32 s93, s33
	s_mov_b32 s94, s8
	s_mov_b32 s95, s9
	s_branch .LBB0_551

; __device__ __forceinline__ void attn_phase(unsigned char* ws, int l, LAS unsigned char* lds, int G) {
;     ...
;     for (int u = vb; u < 768; u += G) {
;         const int pair = u >> 6, qb = u & 63;
;         diff_unit(lds, proj, par + P_SUBN + l * 64, pair >> 2, pair & 3, qb, lam, osc);
;     }
;     __syncthreads();
;     for (int bu = vb; bu < 1152; bu += G) {
;         const int sh = bu >> 6, rem = bu & 63, T0 = (rem >> 1) * 512, rho = (rem & 1) * 8 + wid;
;         dil_unit(lds, proj, sh / 6, sh % 6, T0, rho);
;     }
.LBB0_1231:
	s_bitcmp1_b32 s14, 0
	s_cbranch_scc0 .Lsw1_diff
	s_mov_b32 s92, 1
	s_mov_b32 s93, s60
	s_branch .LBB0_1263
